# hyena_pre: conv3 weights requested before the next tile's prefetch, counted waits, loop-top wait leaves the output stores in flight (on v024)
# speedup vs baseline: 1.0130x; 1.0130x over previous
.LBB0_1304:
	s_lshl_b32 s0, s91, 14
	v_lshlrev_b32_e32 v36, 4, v128
	s_add_i32 s0, s0, 0
	v_lshrrev_b32_e32 v64, 3, v130
	v_and_b32_e32 v56, 0x70, v36
	v_and_b32_e32 v36, 7, v128
	v_add_u32_e32 v37, s0, v56
	v_mov_b32_e32 v57, 0
	v_or_b32_e32 v65, 64, v64
	s_movk_i32 s1, 0x42
	v_mul_u32_u24_e32 v38, 0x90, v130
	v_lshl_add_u32 v39, v36, 4, s0
	v_lshlrev_b32_e32 v36, 3, v36
	v_mul_u32_u24_e32 v40, 0x90, v64
	s_mov_b32 s11, 0
	v_lshl_add_u64 v[58:59], s[16:17], 0, v[56:57]
	v_cmp_gt_u32_e64 s[4:5], s1, v65
	s_waitcnt lgkmcnt(0)
	v_lshl_add_u32 v66, v130, 1, s0
	v_or_b32_e32 v67, 8, v64
	v_or_b32_e32 v68, 16, v64
	v_or_b32_e32 v69, 24, v64
	v_or_b32_e32 v70, 32, v64
	v_or_b32_e32 v71, 40, v64
	v_or_b32_e32 v72, 48, v64
	v_or_b32_e32 v73, 56, v64
	s_lshl_b32 s3, s72, 4
	s_lshl_b32 s12, s80, 1
	s_lshl_b32 s13, s72, 9
	s_lshl_b32 s28, s80, 6
	v_add_u32_e32 v74, v37, v40
	s_movk_i32 s29, 0x800
	s_movk_i32 s30, 0x1800
	v_add_u32_e32 v75, s0, v38
	v_lshlrev_b32_e32 v56, 1, v36
	v_add_u32_e32 v76, v39, v40
	s_mov_b32 s6, s80
	s_waitcnt vmcnt(0)
	s_branch .LBB0_1306

.LBB0_1306:
	s_waitcnt vmcnt(8)
	ds_write_b128 v74, v[0:3]
	ds_write_b128 v74, v[4:7] offset:1152
	ds_write_b128 v74, v[8:11] offset:2304
	ds_write_b128 v74, v[12:15] offset:3456
	ds_write_b128 v74, v[16:19] offset:4608
	ds_write_b128 v74, v[20:23] offset:5760
	ds_write_b128 v74, v[24:27] offset:6912
	ds_write_b128 v74, v[28:31] offset:8064
	s_and_saveexec_b64 s[0:1], s[4:5]
	ds_write_b128 v74, v[32:35] offset:9216
	s_or_b64 exec, exec, s[0:1]
	s_and_b32 s84, s28, 0x7c0
	v_or_b32_e32 v104, s84, v130
	v_lshlrev_b32_e32 v104, 2, v104
	v_mov_b32_e32 v105, 0
	v_lshl_add_u64 v[106:107], s[44:45], 0, v[104:105]
	s_mov_b64 s[86:87], 0x3000
	s_mov_b64 s[88:89], 0x6000
	v_lshl_add_u64 v[108:109], v[106:107], 0, s[86:87]
	v_lshl_add_u64 v[110:111], v[106:107], 0, s[88:89]
	global_load_dword v60, v104, s[44:45]
	global_load_dword v77, v104, s[46:47]
	global_load_dword v61, v[110:111], off
	global_load_dword v62, v[108:109], off
	s_add_i32 s31, s6, s78
	s_cmpk_gt_i32 s31, 0x3fff
	s_cselect_b64 s[22:23], -1, 0
	s_cselect_b32 s85, 0, 9
	s_and_b64 vcc, exec, s[22:23]
	s_cbranch_vccnz .LBB0_1314
	s_add_i32 s0, s3, s12
	s_and_b32 s26, s0, 0x7c0
	s_add_i32 s1, s13, s28
	s_and_b32 s1, s1, 0x7c0
	s_add_i32 s26, s26, -1
	s_lshl_b32 s10, s1, 1
	v_add_u32_e32 v4, s26, v64
	s_and_b32 s7, s0, 0xfffff800
	v_lshl_add_u64 v[36:37], v[58:59], 0, s[10:11]
	v_cmp_gt_u32_e32 vcc, s29, v4
	v_mov_b32_e32 v0, v57
	v_mov_b32_e32 v1, v57
	v_mov_b32_e32 v2, v57
	v_mov_b32_e32 v3, v57
	s_and_saveexec_b64 s[0:1], vcc
	s_cbranch_execz .LBB0_1311
	v_or_b32_e32 v0, s7, v4
	v_mad_i64_i32 v[0:1], s[34:35], v0, s30, v[36:37]
	global_load_dwordx4 v[0:3], v[0:1], off

.LBB0_1314:
	s_and_b32 s36, s28, 0x7c0
	v_or_b32_e32 v36, s36, v130
	v_lshlrev_b32_e32 v36, 2, v36
	v_mov_b32_e32 v37, v57
	v_lshl_add_u64 v[38:39], s[44:45], 0, v[36:37]
	v_add_co_u32_e32 v40, vcc, 0x3000, v38
	s_waitcnt lgkmcnt(0)
	s_mov_b64 s[0:1], vcc
	v_add_co_u32_e32 v42, vcc, 0x6000, v38
	s_cmpk_gt_u32 s36, 0x3ff
	s_nop 0
	v_addc_co_u32_e32 v43, vcc, 0, v39, vcc
	v_addc_co_u32_e64 v41, vcc, 0, v39, s[0:1]
	ds_read_u16 v36, v66
	ds_read_u16 v37, v66 offset:144
	ds_read_u16 v38, v66 offset:288
	ds_read_u16 v39, v66 offset:576
	ds_read_u16 v41, v66 offset:720
	ds_read_u16 v42, v66 offset:864
	ds_read_u16 v44, v66 offset:1008
	ds_read_u16 v40, v66 offset:432
	ds_read_u16 v43, v66 offset:1152
	ds_read_u16 v45, v66 offset:1296
	s_waitcnt lgkmcnt(7)
	v_lshlrev_b32_e32 v38, 16, v38
	v_lshlrev_b32_e32 v36, 16, v36
	v_lshlrev_b32_e32 v82, 16, v37
	s_waitcnt lgkmcnt(6)
	v_lshlrev_b32_e32 v39, 16, v39
	s_waitcnt lgkmcnt(2)
	v_lshlrev_b32_e32 v40, 16, v40
	v_lshlrev_b32_e32 v41, 16, v41
	v_lshlrev_b32_e32 v42, 16, v42
	v_lshlrev_b32_e32 v44, 16, v44
	v_mov_b32_e32 v37, v38
	s_waitcnt lgkmcnt(1)
	v_lshlrev_b32_e32 v43, 16, v43
	s_waitcnt lgkmcnt(0)
	v_lshlrev_b32_e32 v45, 16, v45
	v_mov_b32_e32 v46, v38
	v_mov_b32_e32 v47, v40
	v_mov_b32_e32 v50, v42
	v_mov_b32_e32 v51, v44
	v_pk_mov_b32 v[48:49], v[38:39], v[42:43] op_sel:[1,0]
	s_cselect_b64 s[26:27], -1, 0
	s_mov_b64 s[0:1], -1
	s_and_b64 vcc, exec, s[26:27]
	s_cmp_lg_u32 s85, 0
	s_cbranch_scc1 .Lmy_hp_a
	s_waitcnt vmcnt(1)
	s_branch .Lmy_hp_b
.Lmy_hp_a:
	s_waitcnt vmcnt(8)
.Lmy_hp_b:
	v_pk_mul_f32 v[36:37], v[60:61], v[36:37]
	v_pk_mul_f32 v[52:53], v[60:61], v[38:39]
	v_mov_b32_e32 v63, v61
	v_pk_mul_f32 v[54:55], v[60:61], v[40:41]
	v_pk_mul_f32 v[78:79], v[60:61], v[42:43]
	v_pk_mul_f32 v[80:81], v[60:61], v[44:45]
	s_cmp_lg_u32 s85, 0
	s_cbranch_scc1 .Lmy_hp_c
	s_waitcnt vmcnt(0)
	s_branch .Lmy_hp_d

.Lmy_hp_d:
	v_fma_f32 v36, v62, v82, v36
	v_pk_mul_f32 v[46:47], v[62:63], v[46:47]
	v_fma_f32 v40, v62, v40, v52
	v_fma_f32 v52, v62, v39, v54
	v_pk_mul_f32 v[38:39], v[62:63], v[50:51]
	v_pk_mul_f32 v[48:49], v[60:61], v[48:49]
	v_fma_f32 v44, v62, v44, v78
	v_fma_f32 v50, v62, v43, v80
	v_add_f32_e32 v36, v36, v37
	v_fma_f32 v37, v60, v82, v46
	v_fma_f32 v38, v60, v41, v38
	v_fma_f32 v48, v62, v41, v48
	v_add_f32_e32 v40, v40, v53
	v_add_f32_e32 v46, v52, v55
	v_add_f32_e32 v41, v44, v79
	v_add_f32_e32 v44, v50, v81
	v_add_f32_e32 v37, v37, v47
	v_add_f32_e32 v38, v38, v39
	v_add_f32_e32 v48, v48, v49
	v_add_f32_e32 v36, v77, v36
	v_add_f32_e32 v40, v77, v40
	v_add_f32_e32 v46, v77, v46
	v_add_f32_e32 v39, v77, v41
	v_add_f32_e32 v41, v77, v44
	v_add_f32_e32 v37, v77, v37
	v_add_f32_e32 v38, v77, v38
	v_add_f32_e32 v47, v77, v48
	v_cvt_pk_bf16_f32 v36, v36, v37
	v_cvt_pk_bf16_f32 v37, v40, v46
	v_cvt_pk_bf16_f32 v38, v47, v38
	v_cvt_pk_bf16_f32 v39, v39, v41
	ds_read_u16 v40, v66 offset:1440
	ds_read_u16 v41, v66 offset:1728
	ds_read_u16 v44, v66 offset:1872
	ds_read_u16 v52, v66 offset:2016
	ds_read_u16 v53, v66 offset:2448
	ds_read_u16 v54, v66 offset:2160
	ds_read_u16 v46, v66 offset:1584
	ds_read_u16 v55, v66 offset:2304
	s_waitcnt lgkmcnt(6)
	v_lshlrev_b32_e32 v41, 16, v41
	v_lshlrev_b32_e32 v40, 16, v40
	v_pk_mov_b32 v[42:43], v[42:43], v[40:41] op_sel:[1,0]
	s_waitcnt lgkmcnt(1)
	v_lshlrev_b32_e32 v46, 16, v46
	v_pk_mul_f32 v[42:43], v[60:61], v[42:43]
	v_mov_b32_e32 v50, v40
	v_fma_f32 v42, v62, v45, v42
	v_mov_b32_e32 v51, v46
	v_add_f32_e32 v42, v42, v43
	v_add_f32_e32 v78, v77, v42
	v_pk_mul_f32 v[42:43], v[62:63], v[50:51]
	v_pk_mul_f32 v[48:49], v[60:61], v[40:41]
	v_fma_f32 v42, v60, v45, v42
	v_add_f32_e32 v42, v42, v43
	v_add_f32_e32 v50, v77, v42
	v_fma_f32 v42, v62, v46, v48
	v_lshlrev_b32_e32 v47, 16, v44
	v_add_f32_e32 v42, v42, v49
	v_add_f32_e32 v51, v77, v42
	v_pk_mul_f32 v[42:43], v[60:61], v[46:47]
	s_waitcnt lgkmcnt(0)
	v_lshlrev_b32_e32 v45, 16, v55
	v_lshlrev_b32_e32 v44, 16, v52
	v_fma_f32 v42, v62, v41, v42
	v_pk_mov_b32 v[40:41], v[40:41], v[44:45] op_sel:[1,0]
	v_add_f32_e32 v42, v42, v43
	v_pk_mul_f32 v[40:41], v[60:61], v[40:41]
	v_lshlrev_b32_e32 v48, 16, v54
	v_fma_f32 v40, v62, v47, v40
	v_add_f32_e32 v40, v40, v41
	v_add_f32_e32 v46, v77, v42
	v_add_f32_e32 v52, v77, v40
	v_pk_mul_f32 v[40:41], v[60:61], v[44:45]
	v_mov_b32_e32 v42, v44
	v_mov_b32_e32 v43, v48
	v_pk_mul_f32 v[42:43], v[62:63], v[42:43]
	v_fma_f32 v40, v62, v48, v40
	v_lshlrev_b32_e32 v49, 16, v53
	v_fma_f32 v42, v60, v47, v42
	v_add_f32_e32 v40, v40, v41
	v_add_f32_e32 v42, v42, v43
	v_add_f32_e32 v43, v77, v40
	v_pk_mul_f32 v[40:41], v[60:61], v[48:49]
	v_add_f32_e32 v42, v77, v42
	v_fma_f32 v40, v62, v45, v40
	v_add_f32_e32 v40, v40, v41
	v_add_f32_e32 v47, v77, v40
	v_cvt_pk_bf16_f32 v40, v78, v50
	v_cvt_pk_bf16_f32 v41, v51, v46
	v_cvt_pk_bf16_f32 v42, v52, v42
	v_cvt_pk_bf16_f32 v43, v43, v47
	ds_read_u16 v46, v66 offset:2592
	ds_read_u16 v47, v66 offset:2880
	ds_read_u16 v48, v66 offset:3024
	ds_read_u16 v54, v66 offset:3168
	ds_read_u16 v55, v66 offset:3456
	ds_read_u16 v78, v66 offset:3600
	ds_read_u16 v79, v66 offset:3312
	ds_read_u16 v50, v66 offset:2736
	s_waitcnt lgkmcnt(6)
	v_lshlrev_b32_e32 v47, 16, v47
	v_lshlrev_b32_e32 v46, 16, v46
	v_pk_mov_b32 v[44:45], v[44:45], v[46:47] op_sel:[1,0]
	v_mov_b32_e32 v52, v46
	v_pk_mul_f32 v[44:45], v[60:61], v[44:45]
	s_waitcnt lgkmcnt(0)
	v_lshlrev_b32_e32 v50, 16, v50
	v_fma_f32 v44, v62, v49, v44
	v_add_f32_e32 v44, v44, v45
	v_add_f32_e32 v80, v77, v44
	v_pk_mul_f32 v[44:45], v[60:61], v[46:47]
	v_mov_b32_e32 v53, v50
	v_fma_f32 v44, v62, v50, v44
	v_lshlrev_b32_e32 v51, 16, v48
	v_pk_mul_f32 v[52:53], v[62:63], v[52:53]
	v_add_f32_e32 v44, v44, v45
	v_fma_f32 v48, v60, v49, v52
	v_add_f32_e32 v82, v77, v44
	v_pk_mul_f32 v[44:45], v[60:61], v[50:51]
	v_add_f32_e32 v48, v48, v53
	v_fma_f32 v44, v62, v47, v44
	v_add_f32_e32 v81, v77, v48
	v_add_f32_e32 v44, v44, v45
	v_lshlrev_b32_e32 v49, 16, v55
	v_lshlrev_b32_e32 v48, 16, v54
	v_add_f32_e32 v50, v77, v44
	v_pk_mov_b32 v[44:45], v[46:47], v[48:49] op_sel:[1,0]
	v_lshlrev_b32_e32 v52, 16, v79
	v_pk_mul_f32 v[44:45], v[60:61], v[44:45]
	v_mov_b32_e32 v46, v48
	v_fma_f32 v44, v62, v51, v44
	v_add_f32_e32 v44, v44, v45
	v_add_f32_e32 v54, v77, v44
	v_pk_mul_f32 v[44:45], v[60:61], v[48:49]
	v_mov_b32_e32 v47, v52
	v_pk_mul_f32 v[46:47], v[62:63], v[46:47]
	v_fma_f32 v44, v62, v52, v44
	v_lshlrev_b32_e32 v53, 16, v78
	v_fma_f32 v46, v60, v51, v46
	v_add_f32_e32 v44, v44, v45
	v_add_f32_e32 v46, v46, v47
	v_add_f32_e32 v47, v77, v44
	v_pk_mul_f32 v[44:45], v[60:61], v[52:53]
	v_add_f32_e32 v46, v77, v46
	v_fma_f32 v44, v62, v49, v44
	v_add_f32_e32 v44, v44, v45
	v_add_f32_e32 v51, v77, v44
	v_cvt_pk_bf16_f32 v44, v80, v81
	v_cvt_pk_bf16_f32 v45, v82, v50
	v_cvt_pk_bf16_f32 v46, v54, v46
	v_cvt_pk_bf16_f32 v47, v47, v51
	ds_read_u16 v50, v66 offset:3744
	ds_read_u16 v51, v66 offset:4032
	ds_read_u16 v52, v66 offset:4176
	ds_read_u16 v80, v66 offset:4320
	ds_read_u16 v81, v66 offset:4608
	ds_read_u16 v82, v66 offset:4752
	ds_read_u16 v83, v66 offset:4464
	ds_read_u16 v54, v66 offset:3888
	s_waitcnt lgkmcnt(6)
	v_lshlrev_b32_e32 v51, 16, v51
	v_lshlrev_b32_e32 v50, 16, v50
	v_pk_mov_b32 v[48:49], v[48:49], v[50:51] op_sel:[1,0]
	v_mov_b32_e32 v78, v50
	v_pk_mul_f32 v[48:49], v[60:61], v[48:49]
	s_waitcnt lgkmcnt(0)
	v_lshlrev_b32_e32 v54, 16, v54
	v_fma_f32 v48, v62, v53, v48
	v_add_f32_e32 v48, v48, v49
	v_add_f32_e32 v84, v77, v48
	v_pk_mul_f32 v[48:49], v[60:61], v[50:51]
	v_mov_b32_e32 v79, v54
	v_fma_f32 v48, v62, v54, v48
	v_lshlrev_b32_e32 v55, 16, v52
	v_pk_mul_f32 v[78:79], v[62:63], v[78:79]
	v_add_f32_e32 v48, v48, v49
	v_fma_f32 v52, v60, v53, v78
	v_add_f32_e32 v86, v77, v48
	v_pk_mul_f32 v[48:49], v[60:61], v[54:55]
	v_add_f32_e32 v52, v52, v79
	v_fma_f32 v48, v62, v51, v48
	v_add_f32_e32 v85, v77, v52
	v_add_f32_e32 v48, v48, v49
	v_lshlrev_b32_e32 v53, 16, v81
	v_lshlrev_b32_e32 v52, 16, v80
	v_add_f32_e32 v54, v77, v48
	v_pk_mov_b32 v[48:49], v[50:51], v[52:53] op_sel:[1,0]
	v_lshlrev_b32_e32 v78, 16, v83
	v_pk_mul_f32 v[48:49], v[60:61], v[48:49]
	v_mov_b32_e32 v50, v52
	v_fma_f32 v48, v62, v55, v48
	v_add_f32_e32 v48, v48, v49
	v_add_f32_e32 v80, v77, v48
	v_pk_mul_f32 v[48:49], v[60:61], v[52:53]
	v_mov_b32_e32 v51, v78
	v_pk_mul_f32 v[50:51], v[62:63], v[50:51]
	v_fma_f32 v48, v62, v78, v48
	v_lshlrev_b32_e32 v79, 16, v82
	v_fma_f32 v50, v60, v55, v50
	v_add_f32_e32 v48, v48, v49
	v_add_f32_e32 v50, v50, v51
	v_add_f32_e32 v51, v77, v48
	v_pk_mul_f32 v[48:49], v[60:61], v[78:79]
	v_add_f32_e32 v50, v77, v50
	v_fma_f32 v48, v62, v53, v48
	v_add_f32_e32 v48, v48, v49
	v_add_f32_e32 v55, v77, v48
	v_cvt_pk_bf16_f32 v48, v84, v85
	v_cvt_pk_bf16_f32 v49, v86, v54
	v_cvt_pk_bf16_f32 v50, v80, v50
	v_cvt_pk_bf16_f32 v51, v51, v55
	ds_read_u16 v54, v66 offset:4896
	ds_read_u16 v55, v66 offset:5184
	ds_read_u16 v78, v66 offset:5328
	ds_read_u16 v84, v66 offset:5472
	ds_read_u16 v85, v66 offset:5760
	ds_read_u16 v86, v66 offset:5904
	ds_read_u16 v87, v66 offset:5616
	ds_read_u16 v80, v66 offset:5040
	s_waitcnt lgkmcnt(6)
	v_lshlrev_b32_e32 v55, 16, v55
	v_lshlrev_b32_e32 v54, 16, v54
	v_pk_mov_b32 v[52:53], v[52:53], v[54:55] op_sel:[1,0]
	v_mov_b32_e32 v82, v54
	v_pk_mul_f32 v[52:53], v[60:61], v[52:53]
	s_waitcnt lgkmcnt(0)
	v_lshlrev_b32_e32 v80, 16, v80
	v_fma_f32 v52, v62, v79, v52
	v_add_f32_e32 v52, v52, v53
	v_add_f32_e32 v88, v77, v52
	v_pk_mul_f32 v[52:53], v[60:61], v[54:55]
	v_mov_b32_e32 v83, v80
	v_fma_f32 v52, v62, v80, v52
	v_lshlrev_b32_e32 v81, 16, v78
	v_pk_mul_f32 v[82:83], v[62:63], v[82:83]
	v_add_f32_e32 v52, v52, v53
	v_fma_f32 v78, v60, v79, v82
	v_add_f32_e32 v90, v77, v52
	v_pk_mul_f32 v[52:53], v[60:61], v[80:81]
	v_add_f32_e32 v78, v78, v83
	v_fma_f32 v52, v62, v55, v52
	v_add_f32_e32 v89, v77, v78
	v_add_f32_e32 v52, v52, v53
	v_lshlrev_b32_e32 v79, 16, v85
	v_lshlrev_b32_e32 v78, 16, v84
	v_add_f32_e32 v80, v77, v52
	v_pk_mov_b32 v[52:53], v[54:55], v[78:79] op_sel:[1,0]
	v_lshlrev_b32_e32 v82, 16, v87
	v_pk_mul_f32 v[52:53], v[60:61], v[52:53]
	v_mov_b32_e32 v54, v78
	v_fma_f32 v52, v62, v81, v52
	v_add_f32_e32 v52, v52, v53
	v_add_f32_e32 v84, v77, v52
	v_pk_mul_f32 v[52:53], v[60:61], v[78:79]
	v_mov_b32_e32 v55, v82
	v_pk_mul_f32 v[54:55], v[62:63], v[54:55]
	v_fma_f32 v52, v62, v82, v52
	v_lshlrev_b32_e32 v83, 16, v86
	v_fma_f32 v54, v60, v81, v54
	v_add_f32_e32 v52, v52, v53
	v_add_f32_e32 v54, v54, v55
	v_add_f32_e32 v55, v77, v52
	v_pk_mul_f32 v[52:53], v[60:61], v[82:83]
	v_add_f32_e32 v54, v77, v54
	v_fma_f32 v52, v62, v79, v52
	v_add_f32_e32 v52, v52, v53
	v_add_f32_e32 v81, v77, v52
	v_cvt_pk_bf16_f32 v52, v88, v89
	v_cvt_pk_bf16_f32 v53, v90, v80
	v_cvt_pk_bf16_f32 v54, v84, v54
	v_cvt_pk_bf16_f32 v55, v55, v81
	ds_read_u16 v80, v66 offset:6048
	ds_read_u16 v81, v66 offset:6336
	ds_read_u16 v82, v66 offset:6480
	ds_read_u16 v88, v66 offset:6624
	ds_read_u16 v89, v66 offset:6912
	ds_read_u16 v90, v66 offset:7056
	ds_read_u16 v91, v66 offset:6768
	ds_read_u16 v84, v66 offset:6192
	s_waitcnt lgkmcnt(6)
	v_lshlrev_b32_e32 v81, 16, v81
	v_lshlrev_b32_e32 v80, 16, v80
	v_pk_mov_b32 v[78:79], v[78:79], v[80:81] op_sel:[1,0]
	v_mov_b32_e32 v86, v80
	v_pk_mul_f32 v[78:79], v[60:61], v[78:79]
	s_waitcnt lgkmcnt(0)
	v_lshlrev_b32_e32 v84, 16, v84
	v_fma_f32 v78, v62, v83, v78
	v_add_f32_e32 v78, v78, v79
	v_add_f32_e32 v92, v77, v78
	v_pk_mul_f32 v[78:79], v[60:61], v[80:81]
	v_mov_b32_e32 v87, v84
	v_fma_f32 v78, v62, v84, v78
	v_lshlrev_b32_e32 v85, 16, v82
	v_pk_mul_f32 v[86:87], v[62:63], v[86:87]
	v_add_f32_e32 v78, v78, v79
	v_fma_f32 v82, v60, v83, v86
	v_add_f32_e32 v94, v77, v78
	v_pk_mul_f32 v[78:79], v[60:61], v[84:85]
	v_add_f32_e32 v82, v82, v87
	v_fma_f32 v78, v62, v81, v78
	v_add_f32_e32 v93, v77, v82
	v_add_f32_e32 v78, v78, v79
	v_lshlrev_b32_e32 v83, 16, v89
	v_lshlrev_b32_e32 v82, 16, v88
	v_add_f32_e32 v84, v77, v78
	v_pk_mov_b32 v[78:79], v[80:81], v[82:83] op_sel:[1,0]
	v_lshlrev_b32_e32 v86, 16, v91
	v_pk_mul_f32 v[78:79], v[60:61], v[78:79]
	v_mov_b32_e32 v80, v82
	v_fma_f32 v78, v62, v85, v78
	v_add_f32_e32 v78, v78, v79
	v_add_f32_e32 v88, v77, v78
	v_pk_mul_f32 v[78:79], v[60:61], v[82:83]
	v_mov_b32_e32 v81, v86
	v_pk_mul_f32 v[80:81], v[62:63], v[80:81]
	v_fma_f32 v78, v62, v86, v78
	v_lshlrev_b32_e32 v87, 16, v90
	v_fma_f32 v80, v60, v85, v80
	v_add_f32_e32 v78, v78, v79
	v_add_f32_e32 v80, v80, v81
	v_add_f32_e32 v81, v77, v78
	v_pk_mul_f32 v[78:79], v[60:61], v[86:87]
	v_add_f32_e32 v80, v77, v80
	v_fma_f32 v78, v62, v83, v78
	v_add_f32_e32 v78, v78, v79
	v_add_f32_e32 v85, v77, v78
	v_cvt_pk_bf16_f32 v78, v92, v93
	v_cvt_pk_bf16_f32 v79, v94, v84
	v_cvt_pk_bf16_f32 v80, v88, v80
	v_cvt_pk_bf16_f32 v81, v81, v85
	ds_read_u16 v84, v66 offset:7200
	ds_read_u16 v85, v66 offset:7488
	ds_read_u16 v86, v66 offset:7632
	ds_read_u16 v92, v66 offset:7776
	ds_read_u16 v93, v66 offset:8064
	ds_read_u16 v94, v66 offset:8208
	ds_read_u16 v95, v66 offset:7920
	ds_read_u16 v88, v66 offset:7344
	s_waitcnt lgkmcnt(6)
	v_lshlrev_b32_e32 v85, 16, v85
	v_lshlrev_b32_e32 v84, 16, v84
	v_pk_mov_b32 v[82:83], v[82:83], v[84:85] op_sel:[1,0]
	v_mov_b32_e32 v90, v84
	v_pk_mul_f32 v[82:83], v[60:61], v[82:83]
	s_waitcnt lgkmcnt(0)
	v_lshlrev_b32_e32 v88, 16, v88
	v_fma_f32 v82, v62, v87, v82
	v_add_f32_e32 v82, v82, v83
	v_add_f32_e32 v96, v77, v82
	v_pk_mul_f32 v[82:83], v[60:61], v[84:85]
	v_mov_b32_e32 v91, v88
	v_fma_f32 v82, v62, v88, v82
	v_lshlrev_b32_e32 v89, 16, v86
	v_pk_mul_f32 v[90:91], v[62:63], v[90:91]
	v_add_f32_e32 v82, v82, v83
	v_fma_f32 v86, v60, v87, v90
	v_add_f32_e32 v98, v77, v82
	v_pk_mul_f32 v[82:83], v[60:61], v[88:89]
	v_add_f32_e32 v86, v86, v91
	v_fma_f32 v82, v62, v85, v82
	v_add_f32_e32 v97, v77, v86
	v_add_f32_e32 v82, v82, v83
	v_lshlrev_b32_e32 v87, 16, v93
	v_lshlrev_b32_e32 v86, 16, v92
	v_add_f32_e32 v88, v77, v82
	v_pk_mov_b32 v[82:83], v[84:85], v[86:87] op_sel:[1,0]
	v_lshlrev_b32_e32 v90, 16, v95
	v_pk_mul_f32 v[82:83], v[60:61], v[82:83]
	v_mov_b32_e32 v84, v86
	v_fma_f32 v82, v62, v89, v82
	v_add_f32_e32 v82, v82, v83
	v_add_f32_e32 v92, v77, v82
	v_pk_mul_f32 v[82:83], v[60:61], v[86:87]
	v_mov_b32_e32 v85, v90
	v_pk_mul_f32 v[84:85], v[62:63], v[84:85]
	v_fma_f32 v82, v62, v90, v82
	v_lshlrev_b32_e32 v91, 16, v94
	v_fma_f32 v84, v60, v89, v84
	v_add_f32_e32 v82, v82, v83
	v_add_f32_e32 v84, v84, v85
	v_add_f32_e32 v85, v77, v82
	v_pk_mul_f32 v[82:83], v[60:61], v[90:91]
	v_add_f32_e32 v84, v77, v84
	v_fma_f32 v82, v62, v87, v82
	v_add_f32_e32 v82, v82, v83
	v_add_f32_e32 v89, v77, v82
	v_cvt_pk_bf16_f32 v82, v96, v97
	v_cvt_pk_bf16_f32 v83, v98, v88
	v_cvt_pk_bf16_f32 v84, v92, v84
	v_cvt_pk_bf16_f32 v85, v85, v89
	ds_read_u16 v88, v66 offset:8352
	ds_read_u16 v89, v66 offset:8640
	ds_read_u16 v90, v66 offset:8784
	ds_read_u16 v96, v66 offset:8928
	ds_read_u16 v97, v66 offset:9216
	ds_read_u16 v98, v66 offset:9360
	ds_read_u16 v99, v66 offset:9072
	ds_read_u16 v92, v66 offset:8496
	s_waitcnt lgkmcnt(6)
	v_lshlrev_b32_e32 v89, 16, v89
	v_lshlrev_b32_e32 v88, 16, v88
	v_pk_mov_b32 v[86:87], v[86:87], v[88:89] op_sel:[1,0]
	s_waitcnt lgkmcnt(5)
	v_lshlrev_b32_e32 v93, 16, v90
	v_pk_mul_f32 v[86:87], v[60:61], v[86:87]
	s_waitcnt lgkmcnt(0)
	v_lshlrev_b32_e32 v92, 16, v92
	v_fma_f32 v86, v62, v91, v86
	v_add_f32_e32 v86, v86, v87
	v_add_f32_e32 v100, v77, v86
	v_pk_mul_f32 v[86:87], v[60:61], v[88:89]
	v_mov_b32_e32 v94, v88
	v_fma_f32 v86, v62, v92, v86
	v_add_f32_e32 v86, v86, v87
	v_add_f32_e32 v102, v77, v86
	v_pk_mul_f32 v[86:87], v[60:61], v[92:93]
	v_mov_b32_e32 v95, v92
	v_fma_f32 v86, v62, v89, v86
	v_pk_mul_f32 v[94:95], v[62:63], v[94:95]
	v_add_f32_e32 v86, v86, v87
	v_fma_f32 v90, v60, v91, v94
	v_add_f32_e32 v92, v77, v86
	v_lshlrev_b32_e32 v87, 16, v97
	v_lshlrev_b32_e32 v86, 16, v96
	v_add_f32_e32 v90, v90, v95
	v_pk_mov_b32 v[88:89], v[88:89], v[86:87] op_sel:[1,0]
	v_add_f32_e32 v101, v77, v90
	v_pk_mul_f32 v[88:89], v[60:61], v[88:89]
	v_lshlrev_b32_e32 v90, 16, v99
	v_fma_f32 v88, v62, v93, v88
	v_mov_b32_e32 v94, v86
	v_mov_b32_e32 v95, v90
	v_add_f32_e32 v88, v88, v89
	v_lshlrev_b32_e32 v91, 16, v98
	v_pk_mul_f32 v[94:95], v[62:63], v[94:95]
	v_add_f32_e32 v96, v77, v88
	v_pk_mul_f32 v[88:89], v[60:61], v[86:87]
	v_fma_f32 v63, v60, v93, v94
	v_pk_mul_f32 v[60:61], v[60:61], v[90:91]
	v_add_f32_e32 v63, v63, v95
	v_fma_f32 v86, v62, v90, v88
	v_fma_f32 v60, v62, v87, v60
	v_add_f32_e32 v63, v77, v63
	v_add_f32_e32 v86, v86, v89
	v_add_f32_e32 v60, v60, v61
	v_add_f32_e32 v86, v77, v86
	v_add_f32_e32 v77, v77, v60
	v_cvt_pk_bf16_f32 v60, v100, v101
	v_cvt_pk_bf16_f32 v61, v102, v92
	v_cvt_pk_bf16_f32 v62, v96, v63
	v_cvt_pk_bf16_f32 v63, v86, v77
	s_waitcnt lgkmcnt(0)
	ds_write_b128 v75, v[36:39]
	ds_write_b128 v75, v[40:43] offset:16
	ds_write_b128 v75, v[44:47] offset:32
	ds_write_b128 v75, v[48:51] offset:48
	ds_write_b128 v75, v[52:55] offset:64
	ds_write_b128 v75, v[78:81] offset:80
	ds_write_b128 v75, v[82:85] offset:96
	ds_write_b128 v75, v[60:63] offset:112
	s_waitcnt lgkmcnt(0)
	ds_read_b128 v[36:39], v76
	v_or_b32_e32 v42, s36, v64
	s_cbranch_vccz .LBB0_1316
	v_add_u32_e32 v40, 0xfffffc00, v42
	v_mov_b32_e32 v41, v57
	v_lshlrev_b64 v[40:41], 16, v[40:41]
	v_lshl_add_u64 v[40:41], s[20:21], 0, v[40:41]
	s_mov_b64 s[0:1], 0
